# X3 attention epilogue: batch the 64 serialized gate loads (one wait) instead of load-wait-store per element
# speedup vs baseline: 1.0115x; 1.0115x over previous
; __device__ __forceinline__ float bf2f(unsigned short b) { return __uint_as_float(((unsigned)b) << 16); }
; __device__ __forceinline__ int crow(int r, int hi) { return (r & 3) + 8 * (r >> 2) + 4 * hi; }
; __device__ __forceinline__ void phase_x3(const Args& a, unsigned char* ldsg, int G) {
;     ...
;         if (hi == 0) li_l[r32] = l_reg; asm volatile("s_waitcnt lgkmcnt(0)" ::: "memory");
; #pragma unroll
;         for (int r = 0; r < 16; ++r) { const int orow = crow(r, hi); const float rli = __builtin_amdgcn_rcpf(li_l[orow]); const int grow = R0 + wid * QBLK + orow; const size_t off = (size_t)grow * DM + hb;
; #pragma unroll
;             for (int d0 = 0; d0 < 4; ++d0) { float v = o[d0][r] * rli * bf2f(GBp[off + d0 * 32 + r32]); if (grow < ROW_META) v = 0.f;
;                 const float vn = __shfl_xor(v, 1);
;                 if ((r32 & 1) == 0) *(unsigned*)(OG + off + d0 * 32 + r32) = cvtpk(v, vn); } }
.LBB0_2260:
	s_and_saveexec_b64 s[22:23], s[6:7]
	ds_write_b32 v191, v220
	s_or_b64 exec, exec, s[22:23]
	v_or_b32_e32 v96, s0, v188
	v_ashrrev_i32_e32 v97, 31, v96
	v_lshlrev_b64 v[98:99], 11, v[96:97]
	v_lshl_add_u64 v[98:99], v[98:99], 0, s[40:41]
	v_lshlrev_b64 v[98:99], 1, v[98:99]
	v_lshl_add_u64 v[98:99], v[164:165], 0, v[98:99]
	global_load_ushort v0, v[98:99], off
	global_load_ushort v1, v[98:99], off offset:64
	global_load_ushort v2, v[98:99], off offset:128
	global_load_ushort v3, v[98:99], off offset:192
	v_or_b32_e32 v96, 1, v188
	v_or_b32_e32 v96, s0, v96
	v_ashrrev_i32_e32 v97, 31, v96
	v_lshlrev_b64 v[98:99], 11, v[96:97]
	v_lshl_add_u64 v[98:99], v[98:99], 0, s[40:41]
	v_lshlrev_b64 v[98:99], 1, v[98:99]
	v_lshl_add_u64 v[98:99], v[164:165], 0, v[98:99]
	global_load_ushort v4, v[98:99], off
	global_load_ushort v5, v[98:99], off offset:64
	global_load_ushort v6, v[98:99], off offset:128
	global_load_ushort v7, v[98:99], off offset:192
	v_or_b32_e32 v96, 2, v188
	v_or_b32_e32 v96, s0, v96
	v_ashrrev_i32_e32 v97, 31, v96
	v_lshlrev_b64 v[98:99], 11, v[96:97]
	v_lshl_add_u64 v[98:99], v[98:99], 0, s[40:41]
	v_lshlrev_b64 v[98:99], 1, v[98:99]
	v_lshl_add_u64 v[98:99], v[164:165], 0, v[98:99]
	global_load_ushort v8, v[98:99], off
	global_load_ushort v9, v[98:99], off offset:64
	global_load_ushort v10, v[98:99], off offset:128
	global_load_ushort v11, v[98:99], off offset:192
	v_or_b32_e32 v96, 3, v188
	v_or_b32_e32 v96, s0, v96
	v_ashrrev_i32_e32 v97, 31, v96
	v_lshlrev_b64 v[98:99], 11, v[96:97]
	v_lshl_add_u64 v[98:99], v[98:99], 0, s[40:41]
	v_lshlrev_b64 v[98:99], 1, v[98:99]
	v_lshl_add_u64 v[98:99], v[164:165], 0, v[98:99]
	global_load_ushort v12, v[98:99], off
	global_load_ushort v13, v[98:99], off offset:64
	global_load_ushort v14, v[98:99], off offset:128
	global_load_ushort v15, v[98:99], off offset:192
	v_or_b32_e32 v96, 8, v188
	v_or_b32_e32 v96, s0, v96
	v_ashrrev_i32_e32 v97, 31, v96
	v_lshlrev_b64 v[98:99], 11, v[96:97]
	v_lshl_add_u64 v[98:99], v[98:99], 0, s[40:41]
	v_lshlrev_b64 v[98:99], 1, v[98:99]
	v_lshl_add_u64 v[98:99], v[164:165], 0, v[98:99]
	global_load_ushort v16, v[98:99], off
	global_load_ushort v17, v[98:99], off offset:64
	global_load_ushort v18, v[98:99], off offset:128
	global_load_ushort v19, v[98:99], off offset:192
	v_or_b32_e32 v96, 9, v188
	v_or_b32_e32 v96, s0, v96
	v_ashrrev_i32_e32 v97, 31, v96
	v_lshlrev_b64 v[98:99], 11, v[96:97]
	v_lshl_add_u64 v[98:99], v[98:99], 0, s[40:41]
	v_lshlrev_b64 v[98:99], 1, v[98:99]
	v_lshl_add_u64 v[98:99], v[164:165], 0, v[98:99]
	global_load_ushort v20, v[98:99], off
	global_load_ushort v21, v[98:99], off offset:64
	global_load_ushort v22, v[98:99], off offset:128
	global_load_ushort v23, v[98:99], off offset:192
	v_or_b32_e32 v96, 10, v188
	v_or_b32_e32 v96, s0, v96
	v_ashrrev_i32_e32 v97, 31, v96
	v_lshlrev_b64 v[98:99], 11, v[96:97]
	v_lshl_add_u64 v[98:99], v[98:99], 0, s[40:41]
	v_lshlrev_b64 v[98:99], 1, v[98:99]
	v_lshl_add_u64 v[98:99], v[164:165], 0, v[98:99]
	global_load_ushort v24, v[98:99], off
	global_load_ushort v25, v[98:99], off offset:64
	global_load_ushort v26, v[98:99], off offset:128
	global_load_ushort v27, v[98:99], off offset:192
	v_or_b32_e32 v96, 11, v188
	v_or_b32_e32 v96, s0, v96
	v_ashrrev_i32_e32 v97, 31, v96
	v_lshlrev_b64 v[98:99], 11, v[96:97]
	v_lshl_add_u64 v[98:99], v[98:99], 0, s[40:41]
	v_lshlrev_b64 v[98:99], 1, v[98:99]
	v_lshl_add_u64 v[98:99], v[164:165], 0, v[98:99]
	global_load_ushort v28, v[98:99], off
	global_load_ushort v29, v[98:99], off offset:64
	global_load_ushort v30, v[98:99], off offset:128
	global_load_ushort v31, v[98:99], off offset:192
	v_or_b32_e32 v96, 16, v188
	v_or_b32_e32 v96, s0, v96
	v_ashrrev_i32_e32 v97, 31, v96
	v_lshlrev_b64 v[98:99], 11, v[96:97]
	v_lshl_add_u64 v[98:99], v[98:99], 0, s[40:41]
	v_lshlrev_b64 v[98:99], 1, v[98:99]
	v_lshl_add_u64 v[98:99], v[164:165], 0, v[98:99]
	global_load_ushort v106, v[98:99], off
	global_load_ushort v107, v[98:99], off offset:64
	global_load_ushort v108, v[98:99], off offset:128
	global_load_ushort v109, v[98:99], off offset:192
	v_or_b32_e32 v96, 17, v188
	v_or_b32_e32 v96, s0, v96
	v_ashrrev_i32_e32 v97, 31, v96
	v_lshlrev_b64 v[98:99], 11, v[96:97]
	v_lshl_add_u64 v[98:99], v[98:99], 0, s[40:41]
	v_lshlrev_b64 v[98:99], 1, v[98:99]
	v_lshl_add_u64 v[98:99], v[164:165], 0, v[98:99]
	global_load_ushort v110, v[98:99], off
	global_load_ushort v111, v[98:99], off offset:64
	global_load_ushort v112, v[98:99], off offset:128
	global_load_ushort v113, v[98:99], off offset:192
	v_or_b32_e32 v96, 18, v188
	v_or_b32_e32 v96, s0, v96
	v_ashrrev_i32_e32 v97, 31, v96
	v_lshlrev_b64 v[98:99], 11, v[96:97]
	v_lshl_add_u64 v[98:99], v[98:99], 0, s[40:41]
	v_lshlrev_b64 v[98:99], 1, v[98:99]
	v_lshl_add_u64 v[98:99], v[164:165], 0, v[98:99]
	global_load_ushort v114, v[98:99], off
	global_load_ushort v115, v[98:99], off offset:64
	global_load_ushort v116, v[98:99], off offset:128
	global_load_ushort v117, v[98:99], off offset:192
	v_or_b32_e32 v96, 19, v188
	v_or_b32_e32 v96, s0, v96
	v_ashrrev_i32_e32 v97, 31, v96
	v_lshlrev_b64 v[98:99], 11, v[96:97]
	v_lshl_add_u64 v[98:99], v[98:99], 0, s[40:41]
	v_lshlrev_b64 v[98:99], 1, v[98:99]
	v_lshl_add_u64 v[98:99], v[164:165], 0, v[98:99]
	global_load_ushort v118, v[98:99], off
	global_load_ushort v119, v[98:99], off offset:64
	global_load_ushort v120, v[98:99], off offset:128
	global_load_ushort v121, v[98:99], off offset:192
	v_or_b32_e32 v96, 24, v188
	v_or_b32_e32 v96, s0, v96
	v_ashrrev_i32_e32 v97, 31, v96
	v_lshlrev_b64 v[98:99], 11, v[96:97]
	v_lshl_add_u64 v[98:99], v[98:99], 0, s[40:41]
; __device__ __forceinline__ float bf2f(unsigned short b) { return __uint_as_float(((unsigned)b) << 16); }
; __device__ __forceinline__ int crow(int r, int hi) { return (r & 3) + 8 * (r >> 2) + 4 * hi; }
; __device__ __forceinline__ void phase_x3(const Args& a, unsigned char* ldsg, int G) {
;     ...
;         for (int r = 0; r < 16; ++r) { const int orow = crow(r, hi); const float rli = __builtin_amdgcn_rcpf(li_l[orow]); const int grow = R0 + wid * QBLK + orow; const size_t off = (size_t)grow * DM + hb;
; #pragma unroll
;             for (int d0 = 0; d0 < 4; ++d0) { float v = o[d0][r] * rli * bf2f(GBp[off + d0 * 32 + r32]); if (grow < ROW_META) v = 0.f;
;                 const float vn = __shfl_xor(v, 1);
;                 if ((r32 & 1) == 0) *(unsigned*)(OG + off + d0 * 32 + r32) = cvtpk(v, vn); } }
	v_lshlrev_b64 v[98:99], 1, v[98:99]
	v_lshl_add_u64 v[98:99], v[164:165], 0, v[98:99]
	global_load_ushort v122, v[98:99], off
	global_load_ushort v123, v[98:99], off offset:64
	global_load_ushort v124, v[98:99], off offset:128
	global_load_ushort v125, v[98:99], off offset:192
	v_or_b32_e32 v96, 25, v188
	v_or_b32_e32 v96, s0, v96
	v_ashrrev_i32_e32 v97, 31, v96
	v_lshlrev_b64 v[98:99], 11, v[96:97]
	v_lshl_add_u64 v[98:99], v[98:99], 0, s[40:41]
	v_lshlrev_b64 v[98:99], 1, v[98:99]
	v_lshl_add_u64 v[98:99], v[164:165], 0, v[98:99]
	global_load_ushort v126, v[98:99], off
	global_load_ushort v127, v[98:99], off offset:64
	global_load_ushort v128, v[98:99], off offset:128
	global_load_ushort v129, v[98:99], off offset:192
	v_or_b32_e32 v96, 26, v188
	v_or_b32_e32 v96, s0, v96
	v_ashrrev_i32_e32 v97, 31, v96
	v_lshlrev_b64 v[98:99], 11, v[96:97]
	v_lshl_add_u64 v[98:99], v[98:99], 0, s[40:41]
	v_lshlrev_b64 v[98:99], 1, v[98:99]
	v_lshl_add_u64 v[98:99], v[164:165], 0, v[98:99]
	global_load_ushort v130, v[98:99], off
	global_load_ushort v131, v[98:99], off offset:64
	global_load_ushort v132, v[98:99], off offset:128
	global_load_ushort v133, v[98:99], off offset:192
	v_or_b32_e32 v96, 27, v188
	v_or_b32_e32 v96, s0, v96
	v_ashrrev_i32_e32 v97, 31, v96
	v_lshlrev_b64 v[98:99], 11, v[96:97]
	v_lshl_add_u64 v[98:99], v[98:99], 0, s[40:41]
	v_lshlrev_b64 v[98:99], 1, v[98:99]
	v_lshl_add_u64 v[98:99], v[164:165], 0, v[98:99]
	global_load_ushort v134, v[98:99], off
	global_load_ushort v135, v[98:99], off offset:64
	global_load_ushort v136, v[98:99], off offset:128
	global_load_ushort v137, v[98:99], off offset:192
	v_and_b32_e32 v101, 64, v206
	v_add_u32_e32 v103, 64, v101
	v_xor_b32_e32 v102, 1, v206
	v_cmp_lt_i32_e32 vcc, v102, v103
	s_nop 1
	v_cndmask_b32_e32 v100, v206, v102, vcc
	v_lshlrev_b32_e32 v100, 2, v100
	s_waitcnt vmcnt(0) lgkmcnt(0)
	v_or_b32_e32 v96, s0, v188
	ds_read_b32 v101, v200
	v_ashrrev_i32_e32 v97, 31, v96
	v_lshlrev_b64 v[98:99], 11, v[96:97]
	v_lshl_add_u64 v[98:99], v[98:99], 0, s[40:41]
	v_lshlrev_b64 v[98:99], 1, v[98:99]
	v_lshl_add_u64 v[98:99], v[166:167], 0, v[98:99]
	v_lshlrev_b32_e32 v0, 16, v0
	v_lshlrev_b32_e32 v1, 16, v1
	v_lshlrev_b32_e32 v2, 16, v2
	v_lshlrev_b32_e32 v3, 16, v3
	s_waitcnt lgkmcnt(0)
	v_rcp_f32_e32 v101, v101
	v_cmp_gt_i32_e32 vcc, s64, v96
	s_nop 0
	v_mul_f32_e32 v80, v80, v101
	v_mul_f32_e32 v64, v64, v101
	v_mul_f32_e32 v48, v48, v101
	v_mul_f32_e32 v32, v32, v101
	v_mul_f32_e32 v80, v80, v0
	v_mul_f32_e32 v64, v64, v1
	v_mul_f32_e32 v48, v48, v2
	v_mul_f32_e32 v32, v32, v3
	v_cndmask_b32_e64 v80, v80, 0, vcc
	v_cndmask_b32_e64 v64, v64, 0, vcc
	v_cndmask_b32_e64 v48, v48, 0, vcc
	v_cndmask_b32_e64 v32, v32, 0, vcc
	ds_bpermute_b32 v102, v100, v80
	ds_bpermute_b32 v103, v100, v64
	ds_bpermute_b32 v104, v100, v48
	ds_bpermute_b32 v105, v100, v32
	s_and_saveexec_b64 s[22:23], s[8:9]
	s_waitcnt lgkmcnt(0)
	v_cvt_pk_bf16_f32 v80, v80, v102
	v_cvt_pk_bf16_f32 v64, v64, v103
	v_cvt_pk_bf16_f32 v48, v48, v104
	v_cvt_pk_bf16_f32 v32, v32, v105
	global_store_dword v[98:99], v80, off
	global_store_dword v[98:99], v64, off offset:64
	global_store_dword v[98:99], v48, off offset:128
	global_store_dword v[98:99], v32, off offset:192
	s_or_b64 exec, exec, s[22:23]
	v_or_b32_e32 v96, 1, v188
	v_or_b32_e32 v96, s0, v96
	ds_read_b32 v101, v200 offset:4
	v_ashrrev_i32_e32 v97, 31, v96
	v_lshlrev_b64 v[98:99], 11, v[96:97]
	v_lshl_add_u64 v[98:99], v[98:99], 0, s[40:41]
	v_lshlrev_b64 v[98:99], 1, v[98:99]
	v_lshl_add_u64 v[98:99], v[166:167], 0, v[98:99]
	v_lshlrev_b32_e32 v4, 16, v4
	v_lshlrev_b32_e32 v5, 16, v5
	v_lshlrev_b32_e32 v6, 16, v6
	v_lshlrev_b32_e32 v7, 16, v7
	s_waitcnt lgkmcnt(0)
	v_rcp_f32_e32 v101, v101
	v_cmp_gt_i32_e32 vcc, s64, v96
	s_nop 0
	v_mul_f32_e32 v81, v81, v101
	v_mul_f32_e32 v65, v65, v101
	v_mul_f32_e32 v49, v49, v101
	v_mul_f32_e32 v33, v33, v101
	v_mul_f32_e32 v81, v81, v4
	v_mul_f32_e32 v65, v65, v5
	v_mul_f32_e32 v49, v49, v6
	v_mul_f32_e32 v33, v33, v7
	v_cndmask_b32_e64 v81, v81, 0, vcc
	v_cndmask_b32_e64 v65, v65, 0, vcc
	v_cndmask_b32_e64 v49, v49, 0, vcc
	v_cndmask_b32_e64 v33, v33, 0, vcc
	ds_bpermute_b32 v102, v100, v81
	ds_bpermute_b32 v103, v100, v65
	ds_bpermute_b32 v104, v100, v49
	ds_bpermute_b32 v105, v100, v33
	s_and_saveexec_b64 s[22:23], s[8:9]
	s_waitcnt lgkmcnt(0)
	v_cvt_pk_bf16_f32 v81, v81, v102
	v_cvt_pk_bf16_f32 v65, v65, v103
	v_cvt_pk_bf16_f32 v49, v49, v104
	v_cvt_pk_bf16_f32 v33, v33, v105
	global_store_dword v[98:99], v81, off
	global_store_dword v[98:99], v65, off offset:64
	global_store_dword v[98:99], v49, off offset:128
	global_store_dword v[98:99], v33, off offset:192
	s_or_b64 exec, exec, s[22:23]
	v_or_b32_e32 v96, 2, v188
	v_or_b32_e32 v96, s0, v96
	ds_read_b32 v101, v200 offset:8
	v_ashrrev_i32_e32 v97, 31, v96
	v_lshlrev_b64 v[98:99], 11, v[96:97]
	v_lshl_add_u64 v[98:99], v[98:99], 0, s[40:41]
	v_lshlrev_b64 v[98:99], 1, v[98:99]
	v_lshl_add_u64 v[98:99], v[166:167], 0, v[98:99]
	v_lshlrev_b32_e32 v8, 16, v8
	v_lshlrev_b32_e32 v9, 16, v9
	v_lshlrev_b32_e32 v10, 16, v10
	v_lshlrev_b32_e32 v11, 16, v11
	s_waitcnt lgkmcnt(0)
	v_rcp_f32_e32 v101, v101
	v_cmp_gt_i32_e32 vcc, s64, v96
	s_nop 0
	v_mul_f32_e32 v82, v82, v101
	v_mul_f32_e32 v66, v66, v101
	v_mul_f32_e32 v50, v50, v101
	v_mul_f32_e32 v34, v34, v101
	v_mul_f32_e32 v82, v82, v8
	v_mul_f32_e32 v66, v66, v9
	v_mul_f32_e32 v50, v50, v10
	v_mul_f32_e32 v34, v34, v11
	v_cndmask_b32_e64 v82, v82, 0, vcc
	v_cndmask_b32_e64 v66, v66, 0, vcc
	v_cndmask_b32_e64 v50, v50, 0, vcc
	v_cndmask_b32_e64 v34, v34, 0, vcc
	ds_bpermute_b32 v102, v100, v82
	ds_bpermute_b32 v103, v100, v66
	ds_bpermute_b32 v104, v100, v50
	ds_bpermute_b32 v105, v100, v34
	s_and_saveexec_b64 s[22:23], s[8:9]
	s_waitcnt lgkmcnt(0)
; __device__ __forceinline__ float bf2f(unsigned short b) { return __uint_as_float(((unsigned)b) << 16); }
; __device__ __forceinline__ int crow(int r, int hi) { return (r & 3) + 8 * (r >> 2) + 4 * hi; }
; __device__ __forceinline__ void phase_x3(const Args& a, unsigned char* ldsg, int G) {
;     ...
;         for (int r = 0; r < 16; ++r) { const int orow = crow(r, hi); const float rli = __builtin_amdgcn_rcpf(li_l[orow]); const int grow = R0 + wid * QBLK + orow; const size_t off = (size_t)grow * DM + hb;
; #pragma unroll
;             for (int d0 = 0; d0 < 4; ++d0) { float v = o[d0][r] * rli * bf2f(GBp[off + d0 * 32 + r32]); if (grow < ROW_META) v = 0.f;
;                 const float vn = __shfl_xor(v, 1);
;                 if ((r32 & 1) == 0) *(unsigned*)(OG + off + d0 * 32 + r32) = cvtpk(v, vn); } }
	v_cvt_pk_bf16_f32 v82, v82, v102
	v_cvt_pk_bf16_f32 v66, v66, v103
	v_cvt_pk_bf16_f32 v50, v50, v104
	v_cvt_pk_bf16_f32 v34, v34, v105
	global_store_dword v[98:99], v82, off
	global_store_dword v[98:99], v66, off offset:64
	global_store_dword v[98:99], v50, off offset:128
	global_store_dword v[98:99], v34, off offset:192
	s_or_b64 exec, exec, s[22:23]
	v_or_b32_e32 v96, 3, v188
	v_or_b32_e32 v96, s0, v96
	ds_read_b32 v101, v200 offset:12
	v_ashrrev_i32_e32 v97, 31, v96
	v_lshlrev_b64 v[98:99], 11, v[96:97]
	v_lshl_add_u64 v[98:99], v[98:99], 0, s[40:41]
	v_lshlrev_b64 v[98:99], 1, v[98:99]
	v_lshl_add_u64 v[98:99], v[166:167], 0, v[98:99]
	v_lshlrev_b32_e32 v12, 16, v12
	v_lshlrev_b32_e32 v13, 16, v13
	v_lshlrev_b32_e32 v14, 16, v14
	v_lshlrev_b32_e32 v15, 16, v15
	s_waitcnt lgkmcnt(0)
	v_rcp_f32_e32 v101, v101
	v_cmp_gt_i32_e32 vcc, s64, v96
	s_nop 0
	v_mul_f32_e32 v83, v83, v101
	v_mul_f32_e32 v67, v67, v101
	v_mul_f32_e32 v51, v51, v101
	v_mul_f32_e32 v35, v35, v101
	v_mul_f32_e32 v83, v83, v12
	v_mul_f32_e32 v67, v67, v13
	v_mul_f32_e32 v51, v51, v14
	v_mul_f32_e32 v35, v35, v15
	v_cndmask_b32_e64 v83, v83, 0, vcc
	v_cndmask_b32_e64 v67, v67, 0, vcc
	v_cndmask_b32_e64 v51, v51, 0, vcc
	v_cndmask_b32_e64 v35, v35, 0, vcc
	ds_bpermute_b32 v102, v100, v83
	ds_bpermute_b32 v103, v100, v67
	ds_bpermute_b32 v104, v100, v51
	ds_bpermute_b32 v105, v100, v35
	s_and_saveexec_b64 s[22:23], s[8:9]
	s_waitcnt lgkmcnt(0)
	v_cvt_pk_bf16_f32 v83, v83, v102
	v_cvt_pk_bf16_f32 v67, v67, v103
	v_cvt_pk_bf16_f32 v51, v51, v104
	v_cvt_pk_bf16_f32 v35, v35, v105
	global_store_dword v[98:99], v83, off
	global_store_dword v[98:99], v67, off offset:64
	global_store_dword v[98:99], v51, off offset:128
	global_store_dword v[98:99], v35, off offset:192
	s_or_b64 exec, exec, s[22:23]
	v_or_b32_e32 v96, 8, v188
	v_or_b32_e32 v96, s0, v96
	ds_read_b32 v101, v200 offset:32
	v_ashrrev_i32_e32 v97, 31, v96
	v_lshlrev_b64 v[98:99], 11, v[96:97]
	v_lshl_add_u64 v[98:99], v[98:99], 0, s[40:41]
	v_lshlrev_b64 v[98:99], 1, v[98:99]
	v_lshl_add_u64 v[98:99], v[166:167], 0, v[98:99]
	v_lshlrev_b32_e32 v16, 16, v16
	v_lshlrev_b32_e32 v17, 16, v17
	v_lshlrev_b32_e32 v18, 16, v18
	v_lshlrev_b32_e32 v19, 16, v19
	s_waitcnt lgkmcnt(0)
	v_rcp_f32_e32 v101, v101
	v_cmp_gt_i32_e32 vcc, s64, v96
	s_nop 0
	v_mul_f32_e32 v84, v84, v101
	v_mul_f32_e32 v68, v68, v101
	v_mul_f32_e32 v52, v52, v101
	v_mul_f32_e32 v36, v36, v101
	v_mul_f32_e32 v84, v84, v16
	v_mul_f32_e32 v68, v68, v17
	v_mul_f32_e32 v52, v52, v18
	v_mul_f32_e32 v36, v36, v19
	v_cndmask_b32_e64 v84, v84, 0, vcc
	v_cndmask_b32_e64 v68, v68, 0, vcc
	v_cndmask_b32_e64 v52, v52, 0, vcc
	v_cndmask_b32_e64 v36, v36, 0, vcc
	ds_bpermute_b32 v102, v100, v84
	ds_bpermute_b32 v103, v100, v68
	ds_bpermute_b32 v104, v100, v52
	ds_bpermute_b32 v105, v100, v36
	s_and_saveexec_b64 s[22:23], s[8:9]
	s_waitcnt lgkmcnt(0)
	v_cvt_pk_bf16_f32 v84, v84, v102
	v_cvt_pk_bf16_f32 v68, v68, v103
	v_cvt_pk_bf16_f32 v52, v52, v104
	v_cvt_pk_bf16_f32 v36, v36, v105
	global_store_dword v[98:99], v84, off
	global_store_dword v[98:99], v68, off offset:64
	global_store_dword v[98:99], v52, off offset:128
	global_store_dword v[98:99], v36, off offset:192
	s_or_b64 exec, exec, s[22:23]
	v_or_b32_e32 v96, 9, v188
	v_or_b32_e32 v96, s0, v96
	ds_read_b32 v101, v200 offset:36
	v_ashrrev_i32_e32 v97, 31, v96
	v_lshlrev_b64 v[98:99], 11, v[96:97]
	v_lshl_add_u64 v[98:99], v[98:99], 0, s[40:41]
	v_lshlrev_b64 v[98:99], 1, v[98:99]
	v_lshl_add_u64 v[98:99], v[166:167], 0, v[98:99]
	v_lshlrev_b32_e32 v20, 16, v20
	v_lshlrev_b32_e32 v21, 16, v21
	v_lshlrev_b32_e32 v22, 16, v22
	v_lshlrev_b32_e32 v23, 16, v23
	s_waitcnt lgkmcnt(0)
	v_rcp_f32_e32 v101, v101
	v_cmp_gt_i32_e32 vcc, s64, v96
	s_nop 0
	v_mul_f32_e32 v85, v85, v101
	v_mul_f32_e32 v69, v69, v101
	v_mul_f32_e32 v53, v53, v101
	v_mul_f32_e32 v37, v37, v101
	v_mul_f32_e32 v85, v85, v20
	v_mul_f32_e32 v69, v69, v21
	v_mul_f32_e32 v53, v53, v22
	v_mul_f32_e32 v37, v37, v23
	v_cndmask_b32_e64 v85, v85, 0, vcc
	v_cndmask_b32_e64 v69, v69, 0, vcc
	v_cndmask_b32_e64 v53, v53, 0, vcc
	v_cndmask_b32_e64 v37, v37, 0, vcc
	ds_bpermute_b32 v102, v100, v85
	ds_bpermute_b32 v103, v100, v69
	ds_bpermute_b32 v104, v100, v53
	ds_bpermute_b32 v105, v100, v37
	s_and_saveexec_b64 s[22:23], s[8:9]
	s_waitcnt lgkmcnt(0)
	v_cvt_pk_bf16_f32 v85, v85, v102
	v_cvt_pk_bf16_f32 v69, v69, v103
	v_cvt_pk_bf16_f32 v53, v53, v104
	v_cvt_pk_bf16_f32 v37, v37, v105
	global_store_dword v[98:99], v85, off
	global_store_dword v[98:99], v69, off offset:64
	global_store_dword v[98:99], v53, off offset:128
	global_store_dword v[98:99], v37, off offset:192
	s_or_b64 exec, exec, s[22:23]
	v_or_b32_e32 v96, 10, v188
	v_or_b32_e32 v96, s0, v96
	ds_read_b32 v101, v200 offset:40
	v_ashrrev_i32_e32 v97, 31, v96
	v_lshlrev_b64 v[98:99], 11, v[96:97]
	v_lshl_add_u64 v[98:99], v[98:99], 0, s[40:41]
	v_lshlrev_b64 v[98:99], 1, v[98:99]
	v_lshl_add_u64 v[98:99], v[166:167], 0, v[98:99]
	v_lshlrev_b32_e32 v24, 16, v24
	v_lshlrev_b32_e32 v25, 16, v25
	v_lshlrev_b32_e32 v26, 16, v26
	v_lshlrev_b32_e32 v27, 16, v27
	s_waitcnt lgkmcnt(0)
	v_rcp_f32_e32 v101, v101
	v_cmp_gt_i32_e32 vcc, s64, v96
	s_nop 0
	v_mul_f32_e32 v86, v86, v101
	v_mul_f32_e32 v70, v70, v101
	v_mul_f32_e32 v54, v54, v101
	v_mul_f32_e32 v38, v38, v101
	v_mul_f32_e32 v86, v86, v24
	v_mul_f32_e32 v70, v70, v25
	v_mul_f32_e32 v54, v54, v26
	v_mul_f32_e32 v38, v38, v27
	v_cndmask_b32_e64 v86, v86, 0, vcc
	v_cndmask_b32_e64 v70, v70, 0, vcc
	v_cndmask_b32_e64 v54, v54, 0, vcc
	v_cndmask_b32_e64 v38, v38, 0, vcc
	ds_bpermute_b32 v102, v100, v86
	ds_bpermute_b32 v103, v100, v70
	ds_bpermute_b32 v104, v100, v54
	ds_bpermute_b32 v105, v100, v38
	s_and_saveexec_b64 s[22:23], s[8:9]
	s_waitcnt lgkmcnt(0)
; __device__ __forceinline__ float bf2f(unsigned short b) { return __uint_as_float(((unsigned)b) << 16); }
; __device__ __forceinline__ int crow(int r, int hi) { return (r & 3) + 8 * (r >> 2) + 4 * hi; }
; __device__ __forceinline__ void phase_x3(const Args& a, unsigned char* ldsg, int G) {
;     ...
;         for (int r = 0; r < 16; ++r) { const int orow = crow(r, hi); const float rli = __builtin_amdgcn_rcpf(li_l[orow]); const int grow = R0 + wid * QBLK + orow; const size_t off = (size_t)grow * DM + hb;
; #pragma unroll
;             for (int d0 = 0; d0 < 4; ++d0) { float v = o[d0][r] * rli * bf2f(GBp[off + d0 * 32 + r32]); if (grow < ROW_META) v = 0.f;
;                 const float vn = __shfl_xor(v, 1);
;                 if ((r32 & 1) == 0) *(unsigned*)(OG + off + d0 * 32 + r32) = cvtpk(v, vn); } }
	v_cvt_pk_bf16_f32 v86, v86, v102
	v_cvt_pk_bf16_f32 v70, v70, v103
	v_cvt_pk_bf16_f32 v54, v54, v104
	v_cvt_pk_bf16_f32 v38, v38, v105
	global_store_dword v[98:99], v86, off
	global_store_dword v[98:99], v70, off offset:64
	global_store_dword v[98:99], v54, off offset:128
	global_store_dword v[98:99], v38, off offset:192
	s_or_b64 exec, exec, s[22:23]
	v_or_b32_e32 v96, 11, v188
	v_or_b32_e32 v96, s0, v96
	ds_read_b32 v101, v200 offset:44
	v_ashrrev_i32_e32 v97, 31, v96
	v_lshlrev_b64 v[98:99], 11, v[96:97]
	v_lshl_add_u64 v[98:99], v[98:99], 0, s[40:41]
	v_lshlrev_b64 v[98:99], 1, v[98:99]
	v_lshl_add_u64 v[98:99], v[166:167], 0, v[98:99]
	v_lshlrev_b32_e32 v28, 16, v28
	v_lshlrev_b32_e32 v29, 16, v29
	v_lshlrev_b32_e32 v30, 16, v30
	v_lshlrev_b32_e32 v31, 16, v31
	s_waitcnt lgkmcnt(0)
	v_rcp_f32_e32 v101, v101
	v_cmp_gt_i32_e32 vcc, s64, v96
	s_nop 0
	v_mul_f32_e32 v87, v87, v101
	v_mul_f32_e32 v71, v71, v101
	v_mul_f32_e32 v55, v55, v101
	v_mul_f32_e32 v39, v39, v101
	v_mul_f32_e32 v87, v87, v28
	v_mul_f32_e32 v71, v71, v29
	v_mul_f32_e32 v55, v55, v30
	v_mul_f32_e32 v39, v39, v31
	v_cndmask_b32_e64 v87, v87, 0, vcc
	v_cndmask_b32_e64 v71, v71, 0, vcc
	v_cndmask_b32_e64 v55, v55, 0, vcc
	v_cndmask_b32_e64 v39, v39, 0, vcc
	ds_bpermute_b32 v102, v100, v87
	ds_bpermute_b32 v103, v100, v71
	ds_bpermute_b32 v104, v100, v55
	ds_bpermute_b32 v105, v100, v39
	s_and_saveexec_b64 s[22:23], s[8:9]
	s_waitcnt lgkmcnt(0)
	v_cvt_pk_bf16_f32 v87, v87, v102
	v_cvt_pk_bf16_f32 v71, v71, v103
	v_cvt_pk_bf16_f32 v55, v55, v104
	v_cvt_pk_bf16_f32 v39, v39, v105
	global_store_dword v[98:99], v87, off
	global_store_dword v[98:99], v71, off offset:64
	global_store_dword v[98:99], v55, off offset:128
	global_store_dword v[98:99], v39, off offset:192
	s_or_b64 exec, exec, s[22:23]
	v_or_b32_e32 v96, 16, v188
	v_or_b32_e32 v96, s0, v96
	ds_read_b32 v101, v200 offset:64
	v_ashrrev_i32_e32 v97, 31, v96
	v_lshlrev_b64 v[98:99], 11, v[96:97]
	v_lshl_add_u64 v[98:99], v[98:99], 0, s[40:41]
	v_lshlrev_b64 v[98:99], 1, v[98:99]
	v_lshl_add_u64 v[98:99], v[166:167], 0, v[98:99]
	v_lshlrev_b32_e32 v106, 16, v106
	v_lshlrev_b32_e32 v107, 16, v107
	v_lshlrev_b32_e32 v108, 16, v108
	v_lshlrev_b32_e32 v109, 16, v109
	s_waitcnt lgkmcnt(0)
	v_rcp_f32_e32 v101, v101
	v_cmp_gt_i32_e32 vcc, s64, v96
	s_nop 0
	v_mul_f32_e32 v88, v88, v101
	v_mul_f32_e32 v72, v72, v101
	v_mul_f32_e32 v56, v56, v101
	v_mul_f32_e32 v40, v40, v101
	v_mul_f32_e32 v88, v88, v106
	v_mul_f32_e32 v72, v72, v107
	v_mul_f32_e32 v56, v56, v108
	v_mul_f32_e32 v40, v40, v109
	v_cndmask_b32_e64 v88, v88, 0, vcc
	v_cndmask_b32_e64 v72, v72, 0, vcc
	v_cndmask_b32_e64 v56, v56, 0, vcc
	v_cndmask_b32_e64 v40, v40, 0, vcc
	ds_bpermute_b32 v102, v100, v88
	ds_bpermute_b32 v103, v100, v72
	ds_bpermute_b32 v104, v100, v56
	ds_bpermute_b32 v105, v100, v40
	s_and_saveexec_b64 s[22:23], s[8:9]
	s_waitcnt lgkmcnt(0)
	v_cvt_pk_bf16_f32 v88, v88, v102
	v_cvt_pk_bf16_f32 v72, v72, v103
	v_cvt_pk_bf16_f32 v56, v56, v104
	v_cvt_pk_bf16_f32 v40, v40, v105
	global_store_dword v[98:99], v88, off
	global_store_dword v[98:99], v72, off offset:64
	global_store_dword v[98:99], v56, off offset:128
	global_store_dword v[98:99], v40, off offset:192
	s_or_b64 exec, exec, s[22:23]
	v_or_b32_e32 v96, 17, v188
	v_or_b32_e32 v96, s0, v96
	ds_read_b32 v101, v200 offset:68
	v_ashrrev_i32_e32 v97, 31, v96
	v_lshlrev_b64 v[98:99], 11, v[96:97]
	v_lshl_add_u64 v[98:99], v[98:99], 0, s[40:41]
	v_lshlrev_b64 v[98:99], 1, v[98:99]
	v_lshl_add_u64 v[98:99], v[166:167], 0, v[98:99]
	v_lshlrev_b32_e32 v110, 16, v110
	v_lshlrev_b32_e32 v111, 16, v111
	v_lshlrev_b32_e32 v112, 16, v112
	v_lshlrev_b32_e32 v113, 16, v113
	s_waitcnt lgkmcnt(0)
	v_rcp_f32_e32 v101, v101
	v_cmp_gt_i32_e32 vcc, s64, v96
	s_nop 0
	v_mul_f32_e32 v89, v89, v101
	v_mul_f32_e32 v73, v73, v101
	v_mul_f32_e32 v57, v57, v101
	v_mul_f32_e32 v41, v41, v101
	v_mul_f32_e32 v89, v89, v110
	v_mul_f32_e32 v73, v73, v111
	v_mul_f32_e32 v57, v57, v112
	v_mul_f32_e32 v41, v41, v113
	v_cndmask_b32_e64 v89, v89, 0, vcc
	v_cndmask_b32_e64 v73, v73, 0, vcc
	v_cndmask_b32_e64 v57, v57, 0, vcc
	v_cndmask_b32_e64 v41, v41, 0, vcc
	ds_bpermute_b32 v102, v100, v89
	ds_bpermute_b32 v103, v100, v73
	ds_bpermute_b32 v104, v100, v57
	ds_bpermute_b32 v105, v100, v41
	s_and_saveexec_b64 s[22:23], s[8:9]
	s_waitcnt lgkmcnt(0)
	v_cvt_pk_bf16_f32 v89, v89, v102
	v_cvt_pk_bf16_f32 v73, v73, v103
	v_cvt_pk_bf16_f32 v57, v57, v104
	v_cvt_pk_bf16_f32 v41, v41, v105
	global_store_dword v[98:99], v89, off
	global_store_dword v[98:99], v73, off offset:64
	global_store_dword v[98:99], v57, off offset:128
	global_store_dword v[98:99], v41, off offset:192
	s_or_b64 exec, exec, s[22:23]
	v_or_b32_e32 v96, 18, v188
	v_or_b32_e32 v96, s0, v96
	ds_read_b32 v101, v200 offset:72
	v_ashrrev_i32_e32 v97, 31, v96
	v_lshlrev_b64 v[98:99], 11, v[96:97]
	v_lshl_add_u64 v[98:99], v[98:99], 0, s[40:41]
	v_lshlrev_b64 v[98:99], 1, v[98:99]
	v_lshl_add_u64 v[98:99], v[166:167], 0, v[98:99]
	v_lshlrev_b32_e32 v114, 16, v114
	v_lshlrev_b32_e32 v115, 16, v115
	v_lshlrev_b32_e32 v116, 16, v116
	v_lshlrev_b32_e32 v117, 16, v117
	s_waitcnt lgkmcnt(0)
	v_rcp_f32_e32 v101, v101
	v_cmp_gt_i32_e32 vcc, s64, v96
	s_nop 0
	v_mul_f32_e32 v90, v90, v101
	v_mul_f32_e32 v74, v74, v101
	v_mul_f32_e32 v58, v58, v101
	v_mul_f32_e32 v42, v42, v101
	v_mul_f32_e32 v90, v90, v114
	v_mul_f32_e32 v74, v74, v115
	v_mul_f32_e32 v58, v58, v116
	v_mul_f32_e32 v42, v42, v117
	v_cndmask_b32_e64 v90, v90, 0, vcc
	v_cndmask_b32_e64 v74, v74, 0, vcc
	v_cndmask_b32_e64 v58, v58, 0, vcc
	v_cndmask_b32_e64 v42, v42, 0, vcc
	ds_bpermute_b32 v102, v100, v90
	ds_bpermute_b32 v103, v100, v74
	ds_bpermute_b32 v104, v100, v58
	ds_bpermute_b32 v105, v100, v42
	s_and_saveexec_b64 s[22:23], s[8:9]
	s_waitcnt lgkmcnt(0)
; __device__ __forceinline__ float bf2f(unsigned short b) { return __uint_as_float(((unsigned)b) << 16); }
; __device__ __forceinline__ int crow(int r, int hi) { return (r & 3) + 8 * (r >> 2) + 4 * hi; }
; __device__ __forceinline__ void phase_x3(const Args& a, unsigned char* ldsg, int G) {
;     ...
;         for (int r = 0; r < 16; ++r) { const int orow = crow(r, hi); const float rli = __builtin_amdgcn_rcpf(li_l[orow]); const int grow = R0 + wid * QBLK + orow; const size_t off = (size_t)grow * DM + hb;
; #pragma unroll
;             for (int d0 = 0; d0 < 4; ++d0) { float v = o[d0][r] * rli * bf2f(GBp[off + d0 * 32 + r32]); if (grow < ROW_META) v = 0.f;
;                 const float vn = __shfl_xor(v, 1);
;                 if ((r32 & 1) == 0) *(unsigned*)(OG + off + d0 * 32 + r32) = cvtpk(v, vn); } }
	v_cvt_pk_bf16_f32 v90, v90, v102
	v_cvt_pk_bf16_f32 v74, v74, v103
	v_cvt_pk_bf16_f32 v58, v58, v104
	v_cvt_pk_bf16_f32 v42, v42, v105
	global_store_dword v[98:99], v90, off
	global_store_dword v[98:99], v74, off offset:64
	global_store_dword v[98:99], v58, off offset:128
	global_store_dword v[98:99], v42, off offset:192
	s_or_b64 exec, exec, s[22:23]
	v_or_b32_e32 v96, 19, v188
	v_or_b32_e32 v96, s0, v96
	ds_read_b32 v101, v200 offset:76
	v_ashrrev_i32_e32 v97, 31, v96
	v_lshlrev_b64 v[98:99], 11, v[96:97]
	v_lshl_add_u64 v[98:99], v[98:99], 0, s[40:41]
	v_lshlrev_b64 v[98:99], 1, v[98:99]
	v_lshl_add_u64 v[98:99], v[166:167], 0, v[98:99]
	v_lshlrev_b32_e32 v118, 16, v118
	v_lshlrev_b32_e32 v119, 16, v119
	v_lshlrev_b32_e32 v120, 16, v120
	v_lshlrev_b32_e32 v121, 16, v121
	s_waitcnt lgkmcnt(0)
	v_rcp_f32_e32 v101, v101
	v_cmp_gt_i32_e32 vcc, s64, v96
	s_nop 0
	v_mul_f32_e32 v91, v91, v101
	v_mul_f32_e32 v75, v75, v101
	v_mul_f32_e32 v59, v59, v101
	v_mul_f32_e32 v43, v43, v101
	v_mul_f32_e32 v91, v91, v118
	v_mul_f32_e32 v75, v75, v119
	v_mul_f32_e32 v59, v59, v120
	v_mul_f32_e32 v43, v43, v121
	v_cndmask_b32_e64 v91, v91, 0, vcc
	v_cndmask_b32_e64 v75, v75, 0, vcc
	v_cndmask_b32_e64 v59, v59, 0, vcc
	v_cndmask_b32_e64 v43, v43, 0, vcc
	ds_bpermute_b32 v102, v100, v91
	ds_bpermute_b32 v103, v100, v75
	ds_bpermute_b32 v104, v100, v59
	ds_bpermute_b32 v105, v100, v43
	s_and_saveexec_b64 s[22:23], s[8:9]
	s_waitcnt lgkmcnt(0)
	v_cvt_pk_bf16_f32 v91, v91, v102
	v_cvt_pk_bf16_f32 v75, v75, v103
	v_cvt_pk_bf16_f32 v59, v59, v104
	v_cvt_pk_bf16_f32 v43, v43, v105
	global_store_dword v[98:99], v91, off
	global_store_dword v[98:99], v75, off offset:64
	global_store_dword v[98:99], v59, off offset:128
	global_store_dword v[98:99], v43, off offset:192
	s_or_b64 exec, exec, s[22:23]
	v_or_b32_e32 v96, 24, v188
	v_or_b32_e32 v96, s0, v96
	ds_read_b32 v101, v200 offset:96
	v_ashrrev_i32_e32 v97, 31, v96
	v_lshlrev_b64 v[98:99], 11, v[96:97]
	v_lshl_add_u64 v[98:99], v[98:99], 0, s[40:41]
	v_lshlrev_b64 v[98:99], 1, v[98:99]
	v_lshl_add_u64 v[98:99], v[166:167], 0, v[98:99]
	v_lshlrev_b32_e32 v122, 16, v122
	v_lshlrev_b32_e32 v123, 16, v123
	v_lshlrev_b32_e32 v124, 16, v124
	v_lshlrev_b32_e32 v125, 16, v125
	s_waitcnt lgkmcnt(0)
	v_rcp_f32_e32 v101, v101
	v_cmp_gt_i32_e32 vcc, s64, v96
	s_nop 0
	v_mul_f32_e32 v92, v92, v101
	v_mul_f32_e32 v76, v76, v101
	v_mul_f32_e32 v60, v60, v101
	v_mul_f32_e32 v44, v44, v101
	v_mul_f32_e32 v92, v92, v122
	v_mul_f32_e32 v76, v76, v123
	v_mul_f32_e32 v60, v60, v124
	v_mul_f32_e32 v44, v44, v125
	v_cndmask_b32_e64 v92, v92, 0, vcc
	v_cndmask_b32_e64 v76, v76, 0, vcc
	v_cndmask_b32_e64 v60, v60, 0, vcc
	v_cndmask_b32_e64 v44, v44, 0, vcc
	ds_bpermute_b32 v102, v100, v92
	ds_bpermute_b32 v103, v100, v76
	ds_bpermute_b32 v104, v100, v60
	ds_bpermute_b32 v105, v100, v44
	s_and_saveexec_b64 s[22:23], s[8:9]
	s_waitcnt lgkmcnt(0)
	v_cvt_pk_bf16_f32 v92, v92, v102
	v_cvt_pk_bf16_f32 v76, v76, v103
	v_cvt_pk_bf16_f32 v60, v60, v104
	v_cvt_pk_bf16_f32 v44, v44, v105
	global_store_dword v[98:99], v92, off
	global_store_dword v[98:99], v76, off offset:64
	global_store_dword v[98:99], v60, off offset:128
	global_store_dword v[98:99], v44, off offset:192
	s_or_b64 exec, exec, s[22:23]
	v_or_b32_e32 v96, 25, v188
	v_or_b32_e32 v96, s0, v96
	ds_read_b32 v101, v200 offset:100
	v_ashrrev_i32_e32 v97, 31, v96
	v_lshlrev_b64 v[98:99], 11, v[96:97]
	v_lshl_add_u64 v[98:99], v[98:99], 0, s[40:41]
	v_lshlrev_b64 v[98:99], 1, v[98:99]
	v_lshl_add_u64 v[98:99], v[166:167], 0, v[98:99]
	v_lshlrev_b32_e32 v126, 16, v126
	v_lshlrev_b32_e32 v127, 16, v127
	v_lshlrev_b32_e32 v128, 16, v128
	v_lshlrev_b32_e32 v129, 16, v129
	s_waitcnt lgkmcnt(0)
; __device__ __forceinline__ float bf2f(unsigned short b) { return __uint_as_float(((unsigned)b) << 16); }
; __device__ __forceinline__ int crow(int r, int hi) { return (r & 3) + 8 * (r >> 2) + 4 * hi; }
; __device__ __forceinline__ void phase_x3(const Args& a, unsigned char* ldsg, int G) {
;     ...
;     for (int item = blockIdx.x; item < NITEM; item += G) {
;     ...
;         for (int r = 0; r < 16; ++r) { const int orow = crow(r, hi); const float rli = __builtin_amdgcn_rcpf(li_l[orow]); const int grow = R0 + wid * QBLK + orow; const size_t off = (size_t)grow * DM + hb;
; #pragma unroll
;             for (int d0 = 0; d0 < 4; ++d0) { float v = o[d0][r] * rli * bf2f(GBp[off + d0 * 32 + r32]); if (grow < ROW_META) v = 0.f;
;                 const float vn = __shfl_xor(v, 1);
;                 if ((r32 & 1) == 0) *(unsigned*)(OG + off + d0 * 32 + r32) = cvtpk(v, vn); } }
	v_rcp_f32_e32 v101, v101
	v_cmp_gt_i32_e32 vcc, s64, v96
	s_nop 0
	v_mul_f32_e32 v93, v93, v101
	v_mul_f32_e32 v77, v77, v101
	v_mul_f32_e32 v61, v61, v101
	v_mul_f32_e32 v45, v45, v101
	v_mul_f32_e32 v93, v93, v126
	v_mul_f32_e32 v77, v77, v127
	v_mul_f32_e32 v61, v61, v128
	v_mul_f32_e32 v45, v45, v129
	v_cndmask_b32_e64 v93, v93, 0, vcc
	v_cndmask_b32_e64 v77, v77, 0, vcc
	v_cndmask_b32_e64 v61, v61, 0, vcc
	v_cndmask_b32_e64 v45, v45, 0, vcc
	ds_bpermute_b32 v102, v100, v93
	ds_bpermute_b32 v103, v100, v77
	ds_bpermute_b32 v104, v100, v61
	ds_bpermute_b32 v105, v100, v45
	s_and_saveexec_b64 s[22:23], s[8:9]
	s_waitcnt lgkmcnt(0)
	v_cvt_pk_bf16_f32 v93, v93, v102
	v_cvt_pk_bf16_f32 v77, v77, v103
	v_cvt_pk_bf16_f32 v61, v61, v104
	v_cvt_pk_bf16_f32 v45, v45, v105
	global_store_dword v[98:99], v93, off
	global_store_dword v[98:99], v77, off offset:64
	global_store_dword v[98:99], v61, off offset:128
	global_store_dword v[98:99], v45, off offset:192
	s_or_b64 exec, exec, s[22:23]
	v_or_b32_e32 v96, 26, v188
	v_or_b32_e32 v96, s0, v96
	ds_read_b32 v101, v200 offset:104
	v_ashrrev_i32_e32 v97, 31, v96
	v_lshlrev_b64 v[98:99], 11, v[96:97]
	v_lshl_add_u64 v[98:99], v[98:99], 0, s[40:41]
	v_lshlrev_b64 v[98:99], 1, v[98:99]
	v_lshl_add_u64 v[98:99], v[166:167], 0, v[98:99]
	v_lshlrev_b32_e32 v130, 16, v130
	v_lshlrev_b32_e32 v131, 16, v131
	v_lshlrev_b32_e32 v132, 16, v132
	v_lshlrev_b32_e32 v133, 16, v133
	s_waitcnt lgkmcnt(0)
	v_rcp_f32_e32 v101, v101
	v_cmp_gt_i32_e32 vcc, s64, v96
	s_nop 0
	v_mul_f32_e32 v94, v94, v101
	v_mul_f32_e32 v78, v78, v101
	v_mul_f32_e32 v62, v62, v101
	v_mul_f32_e32 v46, v46, v101
	v_mul_f32_e32 v94, v94, v130
	v_mul_f32_e32 v78, v78, v131
	v_mul_f32_e32 v62, v62, v132
	v_mul_f32_e32 v46, v46, v133
	v_cndmask_b32_e64 v94, v94, 0, vcc
	v_cndmask_b32_e64 v78, v78, 0, vcc
	v_cndmask_b32_e64 v62, v62, 0, vcc
	v_cndmask_b32_e64 v46, v46, 0, vcc
	ds_bpermute_b32 v102, v100, v94
	ds_bpermute_b32 v103, v100, v78
	ds_bpermute_b32 v104, v100, v62
	ds_bpermute_b32 v105, v100, v46
	s_and_saveexec_b64 s[22:23], s[8:9]
	s_waitcnt lgkmcnt(0)
	v_cvt_pk_bf16_f32 v94, v94, v102
	v_cvt_pk_bf16_f32 v78, v78, v103
	v_cvt_pk_bf16_f32 v62, v62, v104
	v_cvt_pk_bf16_f32 v46, v46, v105
	global_store_dword v[98:99], v94, off
	global_store_dword v[98:99], v78, off offset:64
	global_store_dword v[98:99], v62, off offset:128
	global_store_dword v[98:99], v46, off offset:192
	s_or_b64 exec, exec, s[22:23]
	v_or_b32_e32 v96, 27, v188
	v_or_b32_e32 v96, s0, v96
	ds_read_b32 v101, v200 offset:108
	v_ashrrev_i32_e32 v97, 31, v96
	v_lshlrev_b64 v[98:99], 11, v[96:97]
	v_lshl_add_u64 v[98:99], v[98:99], 0, s[40:41]
	v_lshlrev_b64 v[98:99], 1, v[98:99]
	v_lshl_add_u64 v[98:99], v[166:167], 0, v[98:99]
	v_lshlrev_b32_e32 v134, 16, v134
	v_lshlrev_b32_e32 v135, 16, v135
	v_lshlrev_b32_e32 v136, 16, v136
	v_lshlrev_b32_e32 v137, 16, v137
	s_waitcnt lgkmcnt(0)
	v_rcp_f32_e32 v101, v101
	v_cmp_gt_i32_e32 vcc, s64, v96
	s_nop 0
	v_mul_f32_e32 v95, v95, v101
	v_mul_f32_e32 v79, v79, v101
	v_mul_f32_e32 v63, v63, v101
	v_mul_f32_e32 v47, v47, v101
	v_mul_f32_e32 v95, v95, v134
	v_mul_f32_e32 v79, v79, v135
	v_mul_f32_e32 v63, v63, v136
	v_mul_f32_e32 v47, v47, v137
	v_cndmask_b32_e64 v95, v95, 0, vcc
	v_cndmask_b32_e64 v79, v79, 0, vcc
	v_cndmask_b32_e64 v63, v63, 0, vcc
	v_cndmask_b32_e64 v47, v47, 0, vcc
	ds_bpermute_b32 v102, v100, v95
	ds_bpermute_b32 v103, v100, v79
	ds_bpermute_b32 v104, v100, v63
	ds_bpermute_b32 v105, v100, v47
	s_and_saveexec_b64 s[22:23], s[8:9]
	s_waitcnt lgkmcnt(0)
	v_cvt_pk_bf16_f32 v95, v95, v102
	v_cvt_pk_bf16_f32 v79, v79, v103
	v_cvt_pk_bf16_f32 v63, v63, v104
	v_cvt_pk_bf16_f32 v47, v47, v105
	global_store_dword v[98:99], v95, off
	global_store_dword v[98:99], v79, off offset:64
	global_store_dword v[98:99], v63, off offset:128
	global_store_dword v[98:99], v47, off offset:192
	s_or_b64 exec, exec, s[22:23]
	s_branch .LBB0_2193
